# top-k loop: s_nop 0 replaced by the loop-counter decrement (one slot fewer per iteration), on v44
# speedup vs baseline: 1.0107x; 1.0003x over previous
; template <int CTRL> __device__ __forceinline__ unsigned dppu(unsigned x) { return (unsigned)__builtin_amdgcn_mov_dpp((int)x, CTRL, 0xf, 0xf, true); }
; __device__ __forceinline__ unsigned wave_max_u32(unsigned x) {
;     x = max(x, dppu<0xB1>(x)); x = max(x, dppu<0x4E>(x)); x = max(x, dppu<0x141>(x)); x = max(x, dppu<0x140>(x));
;     auto s = __builtin_amdgcn_permlane16_swap(x, x, false, false); x = max((unsigned)s[0], (unsigned)s[1]);
;     auto t = __builtin_amdgcn_permlane32_swap(x, x, false, false); return max((unsigned)t[0], (unsigned)t[1]);
; }
; __device__ __forceinline__ void nsa_block(LAS unsigned char* lds, int b, int g, int t0b, int tid) {
;     ...
;             unsigned sb = 0u;
;             for (int it = 0; it < nsel; ++it) {
;                 const unsigned best = wave_max_u32(max(max(k0, k1), max(k2, k3)));
;                 const int bi = 255 - (int)(best & 0xffu);
;                 if ((bi & 63) == lane) { const int ii = bi >> 6; sb |= 1u << ii; if (ii == 0) k0 = 0u; else if (ii == 1) k1 = 0u; else if (ii == 2) k2 = 0u; else k3 = 0u; }
;             }
.Ltopk_it:
	v_max_u32_e32 v64, v61, v60
	v_max3_u32 v64, v59, v58, v64
	s_nop 1
	v_max_u32_dpp v64, v64, v64 quad_perm:[1,0,3,2] row_mask:0xf bank_mask:0xf bound_ctrl:1
	s_nop 1
	v_max_u32_dpp v64, v64, v64 quad_perm:[2,3,0,1] row_mask:0xf bank_mask:0xf bound_ctrl:1
	s_nop 1
	v_max_u32_dpp v64, v64, v64 row_half_mirror row_mask:0xf bank_mask:0xf bound_ctrl:1
	s_nop 1
	v_max_u32_dpp v64, v64, v64 row_mirror row_mask:0xf bank_mask:0xf bound_ctrl:1
	s_sub_u32 s98, s98, 1
	v_readlane_b32 s60, v64, 0
	v_readlane_b32 s61, v64, 16
	v_readlane_b32 s62, v64, 32
	v_readlane_b32 s63, v64, 48
	s_max_u32 s60, s60, s61
	s_max_u32 s62, s62, s63
	s_max_u32 s60, s60, s62
	v_cmp_eq_u32_e64 s[62:63], v59, s60
	v_cmp_eq_u32_e64 s[64:65], v58, s60
	v_cmp_eq_u32_e64 s[66:67], v61, s60
	v_cmp_eq_u32_e64 s[68:69], v60, s60
	v_cndmask_b32_e64 v59, v59, 0, s[62:63]
	v_cndmask_b32_e64 v58, v58, 0, s[64:65]
	v_cndmask_b32_e64 v61, v61, 0, s[66:67]
	v_cndmask_b32_e64 v60, v60, 0, s[68:69]
	s_cmp_lg_u32 s98, 0
	s_cbranch_scc1 .Ltopk_it
	v_cmp_ne_u32_e64 s[62:63], v59, v250
	v_cmp_ne_u32_e64 s[64:65], v58, v251
	v_cmp_ne_u32_e64 s[66:67], v61, v252
	v_cmp_ne_u32_e64 s[68:69], v60, v253
	v_cndmask_b32_e64 v65, 0, 1, s[62:63]
	v_cndmask_b32_e64 v66, 0, 2, s[64:65]
	v_cndmask_b32_e64 v62, 0, 4, s[66:67]
	v_cndmask_b32_e64 v67, 0, 8, s[68:69]
	v_or3_b32 v62, v62, v65, v66
	v_or_b32_e32 v62, v62, v67
